# attention: softmax (s - m_ref) subtraction folded into the QK^T accumulator init (C = -m_ref); exp2 reads the accumulators directly; update path corrects by the reference change
# baseline (speedup 1.0000x reference)
.LBB0_1258:
	s_bfe_u32 s41, s0, 0x20004
	s_and_b32 s40, s0, 15
	s_lshl_b32 s0, s0, 2
	s_and_b32 s0, s0, 0xffffff00
	v_subrev_u32_e32 v2, s0, v215
	v_add_u32_e32 v206, 0xf00, v2
	v_or_b32_e32 v208, v206, v214
	s_lshl_b32 s8, s41, 12
	v_ashrrev_i32_e32 v209, 31, v208
	v_lshl_add_u64 v[4:5], s[8:9], 0, v[208:209]
	v_mov_b64_e32 v[6:7], s[6:7]
	v_mad_u64_u32 v[6:7], s[10:11], v4, s19, v[6:7]
	v_mad_i32_i24 v7, v5, s19, v7
	s_mul_i32 s8, s40, 0x180
	v_lshl_add_u64 v[4:5], v[6:7], 0, s[8:9]
	v_lshlrev_b32_e32 v0, 1, v180
	v_lshl_add_u64 v[4:5], v[4:5], 0, v[0:1]
	global_load_dwordx4 v[112:115], v[4:5], off
	global_load_dwordx4 v[116:119], v[4:5], off offset:32
	global_load_dwordx4 v[120:123], v[4:5], off offset:64
	global_load_dwordx4 v[124:127], v[4:5], off offset:96
	global_load_dwordx4 v[128:131], v[4:5], off offset:128
	global_load_dwordx4 v[132:135], v[4:5], off offset:160
	global_load_dwordx4 v[136:139], v[4:5], off offset:192
	global_load_dwordx4 v[140:143], v[4:5], off offset:224
	global_load_dwordx4 v[144:147], v[4:5], off offset:256
	global_load_dwordx4 v[148:151], v[4:5], off offset:288
	global_load_dwordx4 v[152:155], v[4:5], off offset:320
	global_load_dwordx4 v[156:159], v[4:5], off offset:352
	s_lshl_b32 s8, s40, 15
	v_add_u32_e32 v0, s18, v216
	v_lshl_add_u64 v[4:5], v[184:185], 0, s[8:9]
	v_readfirstlane_b32 s1, v0
	v_add_u32_e32 v3, 0x2000, v0
	v_lshl_add_u64 v[6:7], v[182:183], 1, v[4:5]
	s_mov_b32 m0, s1
	v_readfirstlane_b32 s1, v3
	v_add_u32_e32 v3, 0x4000, v0
	global_load_lds_dwordx4 v[6:7], off
	v_lshl_add_u64 v[6:7], v[196:197], 1, v[4:5]
	s_mov_b32 m0, s1
	v_readfirstlane_b32 s1, v3
	v_add_u32_e32 v0, 0x6000, v0
	global_load_lds_dwordx4 v[6:7], off
	v_lshl_add_u64 v[6:7], v[198:199], 1, v[4:5]
	s_mov_b32 m0, s1
	v_readfirstlane_b32 s1, v0
	global_load_lds_dwordx4 v[6:7], off
	v_lshl_add_u64 v[4:5], v[200:201], 1, v[4:5]
	s_mov_b32 m0, s1
	s_cmpk_eq_i32 s0, 0x1000
	global_load_lds_dwordx4 v[4:5], off
	s_cbranch_scc1 .LBB0_1269
	s_sub_i32 s0, 0x1000, s0
	s_lshr_b32 s42, s0, 6
	s_mul_i32 s0, s41, 0x180000
	s_add_u32 s0, s3, s0
	s_addc_u32 s1, s14, 0
	s_lshl_b32 s8, s41, 20
	s_add_u32 s10, s15, s8
	s_addc_u32 s11, s16, 0
	v_lshl_add_u64 v[4:5], s[10:11], 0, v[192:193]
	v_lshl_add_u64 v[6:7], s[10:11], 0, v[194:195]
	v_mov_b32_e32 v205, v1
	v_lshl_add_u64 v[210:211], v[4:5], 0, v[204:205]
	v_lshl_add_u64 v[212:213], v[6:7], 0, v[204:205]
	global_load_dwordx4 v[164:167], v[212:213], off
	global_load_dwordx4 v[160:163], v[210:211], off
	global_load_dwordx4 v[176:179], v190, s[0:1]
	global_load_dwordx4 v[168:171], v188, s[0:1]
	global_load_dwordx4 v[172:175], v186, s[0:1]
	v_subrev_u32_e32 v210, s34, v210
	v_subrev_u32_e32 v212, s34, v212
	v_mov_b32_e32 v14, v1
	v_mov_b32_e32 v15, v1
	v_add_u32_e32 v207, 0xf1f, v2
	v_mov_b32_e32 v0, v1
	v_mov_b32_e32 v2, v1
	v_mov_b32_e32 v3, v1
	v_mov_b32_e32 v4, v1
	v_mov_b32_e32 v5, v1
	v_mov_b32_e32 v6, v1
	v_mov_b32_e32 v7, v1
	v_mov_b32_e32 v8, v1
	v_mov_b32_e32 v9, v1
	v_mov_b32_e32 v10, v1
	v_mov_b32_e32 v11, v1
	v_mov_b32_e32 v12, v1
	v_mov_b32_e32 v13, v1
	v_mov_b64_e32 v[78:79], v[14:15]
	v_mov_b64_e32 v[62:63], v[14:15]
	v_mov_b64_e32 v[46:47], v[14:15]
	v_mov_b64_e32 v[30:31], v[14:15]
	s_mov_b32 s43, 0
	v_mov_b32_e32 v209, 0xf149f2ca
	v_mov_b32_e32 v239, 0
	v_mov_b32_e32 v205, 0
	v_mov_b64_e32 v[76:77], v[12:13]
	v_mov_b64_e32 v[74:75], v[10:11]
	v_mov_b64_e32 v[72:73], v[8:9]
	v_mov_b64_e32 v[70:71], v[6:7]
	v_mov_b64_e32 v[68:69], v[4:5]
	v_mov_b64_e32 v[66:67], v[2:3]
	v_mov_b64_e32 v[64:65], v[0:1]
	v_mov_b64_e32 v[60:61], v[12:13]
	v_mov_b64_e32 v[58:59], v[10:11]
	v_mov_b64_e32 v[56:57], v[8:9]
	v_mov_b64_e32 v[54:55], v[6:7]
	v_mov_b64_e32 v[52:53], v[4:5]
	v_mov_b64_e32 v[50:51], v[2:3]
	v_mov_b64_e32 v[48:49], v[0:1]
	v_mov_b64_e32 v[44:45], v[12:13]
	v_mov_b64_e32 v[42:43], v[10:11]
	v_mov_b64_e32 v[40:41], v[8:9]
	v_mov_b64_e32 v[38:39], v[6:7]
	v_mov_b64_e32 v[36:37], v[4:5]
	v_mov_b64_e32 v[34:35], v[2:3]
	v_mov_b64_e32 v[32:33], v[0:1]
	v_mov_b64_e32 v[28:29], v[12:13]
	v_mov_b64_e32 v[26:27], v[10:11]
	v_mov_b64_e32 v[24:25], v[8:9]
	v_mov_b64_e32 v[22:23], v[6:7]
	v_mov_b64_e32 v[20:21], v[4:5]
	v_mov_b64_e32 v[18:19], v[2:3]
	v_mov_b64_e32 v[16:17], v[0:1]
	s_mov_b32 s44, 0
	s_waitcnt vmcnt(0) lgkmcnt(0)
	s_barrier
	ds_write_b128 v236, v[172:175]
	ds_write_b128 v237, v[168:171]
	ds_write_b128 v238, v[176:179]
	ds_write2_b64 v245, v[160:161], v[162:163] offset1:2
	ds_write2_b64 v246, v[164:165], v[166:167] offset1:2
	v_add_u32_e32 v236, 0x1a000, v236
	v_add_u32_e32 v237, 0x1a000, v237
	v_add_u32_e32 v238, 0x1a000, v238
	v_add_u32_e32 v245, 0x4800, v245
	v_add_u32_e32 v246, 0x4800, v246
	s_cmp_lt_u32 s42, 2
	s_cbranch_scc1 .Lattn_p1
	s_mov_b32 s8, 64
	s_mul_i32 s10, s8, 0x180
	s_mul_hi_u32 s11, s8, 0x180
	s_add_u32 s10, s0, s10
	s_addc_u32 s11, s1, s11
	global_load_dwordx4 v[172:175], v186, s[10:11]
	global_load_dwordx4 v[168:171], v188, s[10:11]
	global_load_dwordx4 v[176:179], v190, s[10:11]
	s_lshl_b32 s10, s8, 1
	s_add_u32 s10, s34, s10
	s_addc_u32 s11, s35, 0
	global_load_dwordx4 v[160:163], v210, s[10:11]
	global_load_dwordx4 v[164:167], v212, s[10:11]

.LBB0_1260:
	v_xor_b32_e32 v239, 0x80000000, v209
	v_exp_f32_e32 v0, v96
	v_exp_f32_e32 v6, v97
	v_exp_f32_e32 v7, v98
	v_add_f32_e32 v2, 0, v0
	v_add_f32_e32 v2, v6, v2
	v_add_f32_e32 v14, v7, v2
	v_exp_f32_e32 v15, v99
	v_exp_f32_e32 v96, v100
	v_exp_f32_e32 v97, v101
	v_add_u32_e32 v99, 0x6000, v242
	v_exp_f32_e32 v98, v102
	ds_read_b128 v[2:5], v247
	v_exp_f32_e32 v100, v103
	v_cvt_pk_bf16_f32 v6, v0, v6
	v_add_u32_e32 v0, 0x7000, v242
	ds_read_b128 v[10:13], v247 offset:4608
	v_cvt_pk_bf16_f32 v7, v7, v15
	v_cvt_pk_bf16_f32 v8, v96, v97
	v_cvt_pk_bf16_f32 v9, v98, v100
	v_add_u32_e32 v101, 0x8000, v242
	s_waitcnt lgkmcnt(1)
	v_mfma_f32_32x32x16_bf16 v[64:79], v[2:5], v[6:9], v[64:79]
	v_add_f32_e32 v2, v15, v14
	v_add_f32_e32 v14, v96, v2
	v_exp_f32_e32 v15, v104
	ds_read_b128 v[2:5], v247 offset:9216
	v_add_u32_e32 v104, 0x9000, v242
	s_waitcnt lgkmcnt(1)
	v_mfma_f32_32x32x16_bf16 v[48:63], v[10:13], v[6:9], v[48:63]
	v_exp_f32_e32 v102, v106
	v_exp_f32_e32 v103, v107
	ds_read_b128 v[10:13], v247 offset:13824
	v_exp_f32_e32 v96, v105
	s_waitcnt lgkmcnt(1)
	v_mfma_f32_32x32x16_bf16 v[32:47], v[2:5], v[6:9], v[32:47]
	v_exp_f32_e32 v105, v108
	v_exp_f32_e32 v106, v109
	v_exp_f32_e32 v107, v110
	ds_read_b128 v[2:5], v247 offset:32
	s_waitcnt lgkmcnt(1)
	v_mfma_f32_32x32x16_bf16 v[16:31], v[10:13], v[6:9], v[16:31]
	v_exp_f32_e32 v108, v111
	ds_read_b128 v[10:13], v247 offset:4640
	v_cvt_pk_bf16_f32 v6, v15, v96
	v_cvt_pk_bf16_f32 v7, v102, v103
	v_cvt_pk_bf16_f32 v8, v105, v106
	v_cvt_pk_bf16_f32 v9, v107, v108
	s_waitcnt lgkmcnt(1)
	s_nop 0
	v_mfma_f32_32x32x16_bf16 v[64:79], v[2:5], v[6:9], v[64:79]
	v_add_f32_e32 v2, v97, v14
	v_add_f32_e32 v2, v98, v2
	v_add_f32_e32 v2, v100, v2
	v_add_f32_e32 v14, v15, v2
	v_exp_f32_e32 v15, v80
	ds_read_b128 v[2:5], v247 offset:9248
	s_waitcnt lgkmcnt(1)
	v_mfma_f32_32x32x16_bf16 v[48:63], v[10:13], v[6:9], v[48:63]
	v_exp_f32_e32 v80, v81
	v_exp_f32_e32 v81, v82
	v_exp_f32_e32 v82, v83
	ds_read_b128 v[10:13], v247 offset:13856
	s_waitcnt lgkmcnt(1)
	v_mfma_f32_32x32x16_bf16 v[32:47], v[2:5], v[6:9], v[32:47]
	v_exp_f32_e32 v83, v84
	v_exp_f32_e32 v84, v85
	v_exp_f32_e32 v85, v86
	ds_read_b128 v[2:5], v247 offset:64
	s_waitcnt lgkmcnt(1)
	v_mfma_f32_32x32x16_bf16 v[16:31], v[10:13], v[6:9], v[16:31]
	v_exp_f32_e32 v86, v87
	ds_read_b128 v[10:13], v247 offset:4672
	v_cvt_pk_bf16_f32 v6, v15, v80
	v_cvt_pk_bf16_f32 v7, v81, v82
	v_cvt_pk_bf16_f32 v8, v83, v84
	v_cvt_pk_bf16_f32 v9, v85, v86
	s_waitcnt lgkmcnt(1)
	s_nop 0
	v_mfma_f32_32x32x16_bf16 v[64:79], v[2:5], v[6:9], v[64:79]
	v_add_f32_e32 v2, v96, v14
	v_add_f32_e32 v2, v102, v2
	v_add_f32_e32 v2, v103, v2
	v_add_f32_e32 v14, v105, v2
	v_exp_f32_e32 v87, v88
	ds_read_b128 v[2:5], v247 offset:9280
	s_waitcnt lgkmcnt(1)
	v_mfma_f32_32x32x16_bf16 v[48:63], v[10:13], v[6:9], v[48:63]
	v_exp_f32_e32 v88, v89
	v_exp_f32_e32 v89, v90
	v_exp_f32_e32 v90, v91
	ds_read_b128 v[10:13], v247 offset:13888
	s_waitcnt lgkmcnt(1)
	v_mfma_f32_32x32x16_bf16 v[32:47], v[2:5], v[6:9], v[32:47]
	v_exp_f32_e32 v91, v92
	v_exp_f32_e32 v92, v93
	v_exp_f32_e32 v93, v94
	ds_read_b128 v[2:5], v247 offset:96
	s_waitcnt lgkmcnt(1)
	v_mfma_f32_32x32x16_bf16 v[16:31], v[10:13], v[6:9], v[16:31]
	ds_read_b128 v[10:13], v247 offset:4704
	v_exp_f32_e32 v94, v95
	v_add_f32_e32 v0, v106, v14
	v_add_f32_e32 v0, v107, v0
	v_cvt_pk_bf16_f32 v6, v87, v88
	v_cvt_pk_bf16_f32 v7, v89, v90
	v_cvt_pk_bf16_f32 v8, v91, v92
	v_cvt_pk_bf16_f32 v9, v93, v94
	v_add_f32_e32 v0, v108, v0
	v_add_f32_e32 v0, v15, v0
	s_waitcnt lgkmcnt(1)
	v_mfma_f32_32x32x16_bf16 v[64:79], v[2:5], v[6:9], v[64:79]
	ds_read_b128 v[2:5], v247 offset:9312
	v_add_f32_e32 v0, v80, v0
	v_add_f32_e32 v0, v81, v0
	v_add_f32_e32 v0, v82, v0
	v_add_f32_e32 v0, v83, v0
	v_add_f32_e32 v0, v84, v0
	v_add_f32_e32 v0, v85, v0
	s_waitcnt lgkmcnt(1)
	v_mfma_f32_32x32x16_bf16 v[48:63], v[10:13], v[6:9], v[48:63]
	ds_read_b128 v[10:13], v247 offset:13920
	v_add_f32_e32 v0, v86, v0
	v_add_f32_e32 v0, v87, v0
	v_add_f32_e32 v0, v88, v0
	v_add_f32_e32 v0, v89, v0
	v_add_f32_e32 v0, v90, v0
	v_add_f32_e32 v0, v91, v0
	s_waitcnt lgkmcnt(1)
	v_mfma_f32_32x32x16_bf16 v[32:47], v[2:5], v[6:9], v[32:47]
	v_add_f32_e32 v0, v92, v0
	v_add_f32_e32 v0, v93, v0
	v_add_f32_e32 v0, v94, v0
	v_add_f32_e32 v205, v205, v0
	s_waitcnt lgkmcnt(0)
	v_mfma_f32_32x32x16_bf16 v[16:31], v[10:13], v[6:9], v[16:31]

.LBB0_1264:
	v_cmp_le_i32_e32 vcc, s43, v207
	s_and_saveexec_b64 s[10:11], vcc
	s_cbranch_execz .LBB0_1261
	ds_read_b128 v[2:5], v241
	ds_read_b128 v[6:9], v241 offset:32
	ds_read_b128 v[10:13], v241 offset:64
	ds_read_b128 v[248:251], v241 offset:96
	v_mov_b32_e32 v96, v239
	v_mov_b32_e32 v97, v239
	v_mov_b32_e32 v98, v239
	v_mov_b32_e32 v99, v239
	v_mov_b32_e32 v100, v239
	v_mov_b32_e32 v101, v239
	v_mov_b32_e32 v102, v239
	v_mov_b32_e32 v103, v239
	v_mov_b32_e32 v104, v239
	v_mov_b32_e32 v105, v239
	v_mov_b32_e32 v106, v239
	v_mov_b32_e32 v107, v239
	v_mov_b32_e32 v108, v239
	v_mov_b32_e32 v109, v239
	v_mov_b32_e32 v110, v239
	v_mov_b32_e32 v111, v239
	s_nop 0
	s_waitcnt lgkmcnt(3)
	v_mfma_f32_32x32x16_bf16 v[96:111], v[2:5], v[112:115], v[96:111]
	v_mov_b32_e32 v80, v239
	v_mov_b32_e32 v81, v239
	ds_read_b128 v[2:5], v241 offset:128
	s_waitcnt lgkmcnt(3)
	v_mfma_f32_32x32x16_bf16 v[96:111], v[6:9], v[116:119], v[96:111]
	v_mov_b32_e32 v82, v239
	v_mov_b32_e32 v83, v239
	ds_read_b128 v[6:9], v241 offset:160
	s_waitcnt lgkmcnt(3)
	v_mfma_f32_32x32x16_bf16 v[96:111], v[10:13], v[120:123], v[96:111]
	v_mov_b32_e32 v84, v239
	v_mov_b32_e32 v85, v239
	ds_read_b128 v[10:13], v241 offset:192
	s_waitcnt lgkmcnt(3)
	v_mfma_f32_32x32x16_bf16 v[96:111], v[248:251], v[124:127], v[96:111]
	v_mov_b32_e32 v86, v239
	v_mov_b32_e32 v87, v239
	ds_read_b128 v[248:251], v241 offset:224
	s_waitcnt lgkmcnt(3)
	v_mfma_f32_32x32x16_bf16 v[96:111], v[2:5], v[128:131], v[96:111]
	v_mov_b32_e32 v88, v239
	v_mov_b32_e32 v89, v239
	ds_read_b128 v[2:5], v241 offset:256
	s_waitcnt lgkmcnt(3)
	v_mfma_f32_32x32x16_bf16 v[96:111], v[6:9], v[132:135], v[96:111]
	v_mov_b32_e32 v90, v239
	v_mov_b32_e32 v91, v239
	ds_read_b128 v[6:9], v241 offset:288
	s_waitcnt lgkmcnt(3)
	v_mfma_f32_32x32x16_bf16 v[96:111], v[10:13], v[136:139], v[96:111]
	v_mov_b32_e32 v92, v239
	v_mov_b32_e32 v93, v239
	ds_read_b128 v[10:13], v241 offset:320
	s_waitcnt lgkmcnt(3)
	v_mfma_f32_32x32x16_bf16 v[96:111], v[248:251], v[140:143], v[96:111]
	v_mov_b32_e32 v94, v239
	v_mov_b32_e32 v95, v239
	ds_read_b128 v[248:251], v241 offset:352
	s_waitcnt lgkmcnt(3)
	v_mfma_f32_32x32x16_bf16 v[96:111], v[2:5], v[144:147], v[96:111]
	ds_read_b128 v[2:5], v241 offset:12800
	s_waitcnt lgkmcnt(3)
	v_mfma_f32_32x32x16_bf16 v[96:111], v[6:9], v[148:151], v[96:111]
	ds_read_b128 v[6:9], v241 offset:12832
	s_waitcnt lgkmcnt(3)
	v_mfma_f32_32x32x16_bf16 v[96:111], v[10:13], v[152:155], v[96:111]
	ds_read_b128 v[10:13], v241 offset:12864
	s_waitcnt lgkmcnt(3)
	v_mfma_f32_32x32x16_bf16 v[96:111], v[248:251], v[156:159], v[96:111]
	ds_read_b128 v[248:251], v241 offset:12896
	s_waitcnt lgkmcnt(3)
	v_mfma_f32_32x32x16_bf16 v[80:95], v[2:5], v[112:115], v[80:95]
	ds_read_b128 v[2:5], v241 offset:12928
	s_waitcnt lgkmcnt(3)
	v_mfma_f32_32x32x16_bf16 v[80:95], v[6:9], v[116:119], v[80:95]
	ds_read_b128 v[6:9], v241 offset:12960
	s_waitcnt lgkmcnt(3)
	v_mfma_f32_32x32x16_bf16 v[80:95], v[10:13], v[120:123], v[80:95]
	ds_read_b128 v[10:13], v241 offset:12992
	s_waitcnt lgkmcnt(3)
	v_mfma_f32_32x32x16_bf16 v[80:95], v[248:251], v[124:127], v[80:95]
	ds_read_b128 v[248:251], v241 offset:13024
	s_waitcnt lgkmcnt(3)
	v_mfma_f32_32x32x16_bf16 v[80:95], v[2:5], v[128:131], v[80:95]
	ds_read_b128 v[2:5], v241 offset:13056
	s_waitcnt lgkmcnt(3)
	v_mfma_f32_32x32x16_bf16 v[80:95], v[6:9], v[132:135], v[80:95]
	ds_read_b128 v[6:9], v241 offset:13088
	s_waitcnt lgkmcnt(3)
	v_mfma_f32_32x32x16_bf16 v[80:95], v[10:13], v[136:139], v[80:95]
	ds_read_b128 v[10:13], v241 offset:13120
	s_waitcnt lgkmcnt(3)
	v_mfma_f32_32x32x16_bf16 v[80:95], v[248:251], v[140:143], v[80:95]
	ds_read_b128 v[248:251], v241 offset:13152
	s_waitcnt lgkmcnt(3)
	v_mfma_f32_32x32x16_bf16 v[80:95], v[2:5], v[144:147], v[80:95]
	s_waitcnt lgkmcnt(2)
	v_mfma_f32_32x32x16_bf16 v[80:95], v[6:9], v[148:151], v[80:95]
	s_waitcnt lgkmcnt(1)
	v_mfma_f32_32x32x16_bf16 v[80:95], v[10:13], v[152:155], v[80:95]
	s_waitcnt lgkmcnt(0)
	v_mfma_f32_32x32x16_bf16 v[80:95], v[248:251], v[156:159], v[80:95]
	s_add_i32 s8, s43, 63
	v_cmp_gt_i32_e32 vcc, s8, v206
	s_and_saveexec_b64 s[12:13], vcc
	s_cbranch_execz .LBB0_1267
	v_add_u32_e32 v0, s43, v217
	v_cmp_gt_i32_e32 vcc, v0, v208
	s_nop 1
	v_cndmask_b32_e32 v2, v96, v244, vcc
	v_cmp_lt_i32_e32 vcc, v0, v208
	s_nop 1
	v_cndmask_b32_e32 v96, v2, v96, vcc
	v_add_u32_e32 v2, 2, v0
	v_cndmask_b32_e32 v97, v244, v97, vcc
	v_cmp_le_i32_e32 vcc, v2, v208
	v_add_u32_e32 v2, 3, v0
	s_nop 0
	v_cndmask_b32_e32 v98, v244, v98, vcc
	v_cmp_le_i32_e32 vcc, v2, v208
	v_add_u32_e32 v2, 8, v0
	s_nop 0
	v_cndmask_b32_e32 v99, v244, v99, vcc
	v_cmp_le_i32_e32 vcc, v2, v208
	v_add_u32_e32 v2, 9, v0
	s_nop 0
	v_cndmask_b32_e32 v100, v244, v100, vcc
	v_cmp_le_i32_e32 vcc, v2, v208
	v_add_u32_e32 v2, 10, v0
	s_nop 0
	v_cndmask_b32_e32 v101, v244, v101, vcc
	v_cmp_le_i32_e32 vcc, v2, v208
	v_add_u32_e32 v2, 11, v0
	s_nop 0
	v_cndmask_b32_e32 v102, v244, v102, vcc
	v_cmp_le_i32_e32 vcc, v2, v208
	v_add_u32_e32 v2, 16, v0
	s_nop 0
	v_cndmask_b32_e32 v103, v244, v103, vcc
	v_cmp_le_i32_e32 vcc, v2, v208
	v_add_u32_e32 v2, 17, v0
	s_nop 0
	v_cndmask_b32_e32 v104, v244, v104, vcc
	v_cmp_le_i32_e32 vcc, v2, v208
	v_add_u32_e32 v2, 18, v0
	s_nop 0
	v_cndmask_b32_e32 v105, v244, v105, vcc
	v_cmp_le_i32_e32 vcc, v2, v208
	v_add_u32_e32 v2, 19, v0
	s_nop 0
	v_cndmask_b32_e32 v106, v244, v106, vcc
	v_cmp_le_i32_e32 vcc, v2, v208
	v_add_u32_e32 v2, 24, v0
	s_nop 0
	v_cndmask_b32_e32 v107, v244, v107, vcc
	v_cmp_le_i32_e32 vcc, v2, v208
	v_add_u32_e32 v2, 25, v0
	s_nop 0
	v_cndmask_b32_e32 v108, v244, v108, vcc
	v_cmp_le_i32_e32 vcc, v2, v208
	v_add_u32_e32 v2, 26, v0
	s_nop 0
	v_cndmask_b32_e32 v109, v244, v109, vcc
	v_cmp_le_i32_e32 vcc, v2, v208
	v_add_u32_e32 v2, 27, v0
	s_nop 0
	v_cndmask_b32_e32 v110, v244, v110, vcc
	v_cmp_le_i32_e32 vcc, v2, v208
	v_add_u32_e32 v2, 32, v0
	s_nop 0
	v_cndmask_b32_e32 v111, v244, v111, vcc
	v_cmp_le_i32_e32 vcc, v2, v208
	v_add_u32_e32 v2, 33, v0
	s_nop 0
	v_cndmask_b32_e32 v80, v244, v80, vcc
	v_cmp_le_i32_e32 vcc, v2, v208
	v_add_u32_e32 v2, 34, v0
	s_nop 0
	v_cndmask_b32_e32 v81, v244, v81, vcc
	v_cmp_le_i32_e32 vcc, v2, v208
	v_add_u32_e32 v2, 35, v0
	s_nop 0
	v_cndmask_b32_e32 v82, v244, v82, vcc
	v_cmp_le_i32_e32 vcc, v2, v208
	v_add_u32_e32 v2, 40, v0
	s_nop 0
	v_cndmask_b32_e32 v83, v244, v83, vcc
	v_cmp_le_i32_e32 vcc, v2, v208
	v_add_u32_e32 v2, 41, v0
	s_nop 0
	v_cndmask_b32_e32 v84, v244, v84, vcc
	v_cmp_le_i32_e32 vcc, v2, v208
	v_add_u32_e32 v2, 42, v0
	s_nop 0
	v_cndmask_b32_e32 v85, v244, v85, vcc
	v_cmp_le_i32_e32 vcc, v2, v208
	v_add_u32_e32 v2, 43, v0
	s_nop 0
	v_cndmask_b32_e32 v86, v244, v86, vcc
	v_cmp_le_i32_e32 vcc, v2, v208
	v_add_u32_e32 v2, 48, v0
	s_nop 0
	v_cndmask_b32_e32 v87, v244, v87, vcc
	v_cmp_le_i32_e32 vcc, v2, v208
	v_add_u32_e32 v2, 49, v0
	s_nop 0
	v_cndmask_b32_e32 v88, v244, v88, vcc
	v_cmp_le_i32_e32 vcc, v2, v208
	v_add_u32_e32 v2, 50, v0
	s_nop 0
	v_cndmask_b32_e32 v89, v244, v89, vcc
	v_cmp_le_i32_e32 vcc, v2, v208
	v_add_u32_e32 v2, 51, v0
	s_nop 0
	v_cndmask_b32_e32 v90, v244, v90, vcc
	v_cmp_le_i32_e32 vcc, v2, v208
	v_add_u32_e32 v2, 56, v0
	s_nop 0
	v_cndmask_b32_e32 v91, v244, v91, vcc
	v_cmp_le_i32_e32 vcc, v2, v208
	v_add_u32_e32 v2, 57, v0
	s_nop 0
	v_cndmask_b32_e32 v92, v244, v92, vcc
	v_cmp_le_i32_e32 vcc, v2, v208
	v_add_u32_e32 v2, 58, v0
	v_add_u32_e32 v0, 59, v0
	v_cndmask_b32_e32 v93, v244, v93, vcc
	v_cmp_le_i32_e32 vcc, v2, v208
	s_nop 1
	v_cndmask_b32_e32 v94, v244, v94, vcc
	v_cmp_le_i32_e32 vcc, v0, v208
	s_nop 1
	v_cndmask_b32_e32 v95, v244, v95, vcc
.LBB0_1267:
	s_or_b64 exec, exec, s[12:13]
	v_max3_f32 v0, v96, s22, v97
	v_max3_f32 v0, v0, v98, v99
	v_max3_f32 v0, v0, v100, v101
	v_max3_f32 v0, v0, v102, v103
	v_max3_f32 v0, v0, v104, v105
	v_max3_f32 v0, v0, v106, v107
	v_max3_f32 v0, v0, v108, v109
	v_max3_f32 v0, v0, v110, v111
	v_max3_f32 v0, v0, v80, v81
	v_max3_f32 v0, v0, v82, v83
	v_max3_f32 v0, v0, v84, v85
	v_max3_f32 v0, v0, v86, v87
	v_max3_f32 v0, v0, v88, v89
	v_max3_f32 v0, v0, v90, v91
	v_max3_f32 v0, v0, v92, v93
	v_max3_f32 v0, v0, v94, v95
	v_mov_b32_e32 v2, v0
	s_nop 1
	v_permlane32_swap_b32_e32 v2, v0
	s_nop 0
	v_max_f32_e32 v2, v2, v2
	v_max_f32_e32 v0, v0, v2
	v_sub_f32_e32 v0, v0, v239
	v_sub_f32_e32 v2, v0, v209
	v_cmp_ge_f32_e32 vcc, s23, v2
	s_cmp_eq_u64 vcc, exec
	s_cbranch_scc1 .LBB0_1260
	v_max_f32_e32 v0, v0, v0
	v_max_f32_e32 v2, v209, v209
	v_max_f32_e32 v2, v2, v0
	v_sub_f32_e32 v0, v209, v2
	v_exp_f32_e32 v0, v0
	v_mov_b32_e32 v209, v2
	v_add_f32_e32 v2, v2, v239
	v_sub_f32_e32 v96, v96, v2
	v_sub_f32_e32 v97, v97, v2
	v_sub_f32_e32 v98, v98, v2
	v_sub_f32_e32 v99, v99, v2
	v_sub_f32_e32 v100, v100, v2
	v_sub_f32_e32 v101, v101, v2
	v_sub_f32_e32 v102, v102, v2
	v_sub_f32_e32 v103, v103, v2
	v_sub_f32_e32 v104, v104, v2
	v_sub_f32_e32 v105, v105, v2
	v_sub_f32_e32 v106, v106, v2
	v_sub_f32_e32 v107, v107, v2
	v_sub_f32_e32 v108, v108, v2
	v_sub_f32_e32 v109, v109, v2
	v_sub_f32_e32 v110, v110, v2
	v_sub_f32_e32 v111, v111, v2
	v_sub_f32_e32 v80, v80, v2
	v_sub_f32_e32 v81, v81, v2
	v_sub_f32_e32 v82, v82, v2
	v_sub_f32_e32 v83, v83, v2
	v_sub_f32_e32 v84, v84, v2
	v_sub_f32_e32 v85, v85, v2
	v_sub_f32_e32 v86, v86, v2
	v_sub_f32_e32 v87, v87, v2
	v_sub_f32_e32 v88, v88, v2
	v_sub_f32_e32 v89, v89, v2
	v_sub_f32_e32 v90, v90, v2
	v_sub_f32_e32 v91, v91, v2
	v_sub_f32_e32 v92, v92, v2
	v_sub_f32_e32 v93, v93, v2
	v_sub_f32_e32 v94, v94, v2
	v_sub_f32_e32 v95, v95, v2
	v_pk_mul_f32 v[78:79], v[78:79], v[0:1] op_sel_hi:[1,0]
	v_pk_mul_f32 v[76:77], v[76:77], v[0:1] op_sel_hi:[1,0]
	v_pk_mul_f32 v[74:75], v[74:75], v[0:1] op_sel_hi:[1,0]
	v_pk_mul_f32 v[72:73], v[72:73], v[0:1] op_sel_hi:[1,0]
	v_pk_mul_f32 v[70:71], v[70:71], v[0:1] op_sel_hi:[1,0]
	v_pk_mul_f32 v[68:69], v[68:69], v[0:1] op_sel_hi:[1,0]
	v_pk_mul_f32 v[66:67], v[66:67], v[0:1] op_sel_hi:[1,0]
	v_pk_mul_f32 v[64:65], v[64:65], v[0:1] op_sel_hi:[1,0]
	v_pk_mul_f32 v[62:63], v[62:63], v[0:1] op_sel_hi:[1,0]
	v_pk_mul_f32 v[60:61], v[60:61], v[0:1] op_sel_hi:[1,0]
	v_pk_mul_f32 v[58:59], v[58:59], v[0:1] op_sel_hi:[1,0]
	v_pk_mul_f32 v[56:57], v[56:57], v[0:1] op_sel_hi:[1,0]
	v_pk_mul_f32 v[54:55], v[54:55], v[0:1] op_sel_hi:[1,0]
	v_pk_mul_f32 v[52:53], v[52:53], v[0:1] op_sel_hi:[1,0]
	v_pk_mul_f32 v[50:51], v[50:51], v[0:1] op_sel_hi:[1,0]
	v_pk_mul_f32 v[48:49], v[48:49], v[0:1] op_sel_hi:[1,0]
	v_pk_mul_f32 v[46:47], v[46:47], v[0:1] op_sel_hi:[1,0]
	v_pk_mul_f32 v[44:45], v[44:45], v[0:1] op_sel_hi:[1,0]
	v_pk_mul_f32 v[42:43], v[42:43], v[0:1] op_sel_hi:[1,0]
	v_pk_mul_f32 v[40:41], v[40:41], v[0:1] op_sel_hi:[1,0]
	v_pk_mul_f32 v[38:39], v[38:39], v[0:1] op_sel_hi:[1,0]
	v_pk_mul_f32 v[36:37], v[36:37], v[0:1] op_sel_hi:[1,0]
	v_pk_mul_f32 v[34:35], v[34:35], v[0:1] op_sel_hi:[1,0]
	v_pk_mul_f32 v[32:33], v[32:33], v[0:1] op_sel_hi:[1,0]
	v_pk_mul_f32 v[30:31], v[30:31], v[0:1] op_sel_hi:[1,0]
	v_pk_mul_f32 v[28:29], v[28:29], v[0:1] op_sel_hi:[1,0]
	v_pk_mul_f32 v[26:27], v[26:27], v[0:1] op_sel_hi:[1,0]
	v_pk_mul_f32 v[24:25], v[24:25], v[0:1] op_sel_hi:[1,0]
	v_pk_mul_f32 v[22:23], v[22:23], v[0:1] op_sel_hi:[1,0]
	v_pk_mul_f32 v[20:21], v[20:21], v[0:1] op_sel_hi:[1,0]
	v_pk_mul_f32 v[18:19], v[18:19], v[0:1] op_sel_hi:[1,0]
	v_pk_mul_f32 v[16:17], v[16:17], v[0:1] op_sel_hi:[1,0]
	v_mul_f32_e32 v205, v205, v0
	s_branch .LBB0_1260
